# SGU item: pass A row loads and pass C mixing-weight loads prefetched one iteration ahead (were load-wait-use per iteration)
# speedup vs baseline: 1.0160x; 1.0019x over previous
; #define LAS __attribute__((address_space(3)))
; __device__ __forceinline__ void sgu_item(LAS unsigned char* lds, const bf16* PROJ, bf16* MIX, const float* lg, const float* lb, const float* ws_, const float* bs_, int item, int tid) {
;     const int lane = tid & 63, wid = __builtin_amdgcn_readfirstlane(tid >> 6), r32 = lane & 31, hi = lane >> 5;
;     const size_t row0 = (size_t)item * 128;
;     LAS float* st = (LAS float*)lds;
;     LAS unsigned char* vnT = lds + 1024;
;     for (int q = 0; q < 16; ++q) { const int s = 16 * wid + q; const u32x4 v = *(const u32x4*)(PROJ + (row0 + s) * NPROJ + 512 + lane * 8);
.LBB0_357:
	s_and_b64 vcc, exec, s[0:1]
	s_cbranch_vccz .LBB0_366
	v_readfirstlane_b32 s2, v200
	s_ashr_i32 s0, s2, 6
	s_lshl_b32 s4, s0, 7
	s_ashr_i32 s25, s24, 31
	s_lshl_b32 s1, s0, 4
	s_add_i32 s4, s4, 0
	s_mul_i32 s6, s24, 0xa0000
	s_mul_i32 s0, s0, 0x14000
	s_load_dwordx8 s[16:23], s[78:79], 0x68
	s_mul_hi_i32 s5, s24, 0xa0000
	s_mul_hi_i32 s1, s1, 0x1400
	s_add_u32 s0, s6, s0
	v_and_b32_e32 v2, 63, v200
	s_addc_u32 s1, s5, s1
	v_readlane_b32 s5, v255, 26
	v_lshlrev_b32_e32 v0, 2, v2
	s_add_u32 s0, s5, s0
	v_readlane_b32 s5, v255, 27
	v_xor_b32_e32 v3, 4, v0
	v_xor_b32_e32 v8, 8, v0
	v_xor_b32_e32 v9, 16, v0
	v_xor_b32_e32 v10, 32, v0
	v_xor_b32_e32 v11, 64, v0
	v_xor_b32_e32 v12, 0x80, v0
	v_lshlrev_b32_e32 v0, 4, v2
	s_addc_u32 s1, s5, s1
	s_mov_b32 s3, 0
	v_cmp_eq_u32_e64 s[8:9], 0, v2
	v_lshl_add_u64 v[4:5], s[0:1], 0, v[0:1]
	s_mov_b64 s[100:101], 0x1400
	global_load_dwordx4 v[108:111], v[4:5], off
	s_branch .LBB0_360

; __device__ __forceinline__ float bflo(unsigned u) { return __uint_as_float(u << 16); }
; __device__ __forceinline__ float bfhi(unsigned u) { return __uint_as_float(u & 0xffff0000u); }
; __device__ __forceinline__ float geluf_(float x) { const float y = 0.7978845608028654f * (x + 0.044715f * x * x * x); return x * sigmoidf_(2.0f * y); }
; __device__ __forceinline__ void sgu_item(LAS unsigned char* lds, const bf16* PROJ, bf16* MIX, const float* lg, const float* lb, const float* ws_, const float* bs_, int item, int tid) {
;     ...
;     for (int q = 0; q < 16; ++q) { const int s = 16 * wid + q; const u32x4 v = *(const u32x4*)(PROJ + (row0 + s) * NPROJ + 512 + lane * 8);
;         float x[8] = {bflo(v.x), bfhi(v.x), bflo(v.y), bfhi(v.y), bflo(v.z), bfhi(v.z), bflo(v.w), bfhi(v.w)}; float sm = 0.f;
; #pragma unroll
;         for (int e = 0; e < 8; ++e) { x[e] = geluf_(x[e]); sm += x[e]; }
;         const float mean = wave_sum(sm, lane) * (1.f / 512.f); float s2 = 0.f;
; #pragma unroll
;         for (int e = 0; e < 8; ++e) { const float d = x[e] - mean; s2 += d * d; }
;         const float rstd = 1.0f / sqrtf(wave_sum(s2, lane) * (1.f / 512.f) + 1e-5f);
;         if (lane == 0) { st[2 * s] = mean; st[2 * s + 1] = rstd; } }
.LBB0_360:
	s_waitcnt vmcnt(0)
	v_mov_b32_e32 v14, v108
	v_mov_b32_e32 v15, v109
	v_mov_b32_e32 v16, v110
	v_mov_b32_e32 v17, v111
	v_lshl_add_u64 v[112:113], v[4:5], 0, s[100:101]
	global_load_dwordx4 v[108:111], v[112:113], off
	v_lshlrev_b32_e32 v0, 16, v14
	s_waitcnt lgkmcnt(0)
	v_and_b32_e32 v7, 0xffff0000, v14
	v_mul_f32_e32 v6, 0x3d372713, v0
	v_lshlrev_b32_e32 v13, 16, v15
	v_mul_f32_e32 v19, 0x3d372713, v7
	v_mul_f32_e32 v6, v6, v0
	v_and_b32_e32 v14, 0xffff0000, v15
	v_mul_f32_e32 v20, 0x3d372713, v13
	v_mul_f32_e32 v19, v19, v7
	v_fma_f32 v6, v6, v0, v0
	v_lshlrev_b32_e32 v15, 16, v16
	v_mul_f32_e32 v21, 0x3d372713, v14
	v_mul_f32_e32 v20, v20, v13
	v_fma_f32 v19, v19, v7, v7
	v_mul_f32_e32 v6, 0x3f4c422a, v6
	v_and_b32_e32 v16, 0xffff0000, v16
	v_mul_f32_e32 v22, 0x3d372713, v15
	v_mul_f32_e32 v21, v21, v14
	v_fma_f32 v20, v20, v13, v13
	v_mul_f32_e32 v19, 0x3f4c422a, v19
	v_add_f32_e32 v6, v6, v6
	v_lshlrev_b32_e32 v18, 16, v17
	v_mul_f32_e32 v23, 0x3d372713, v16
	v_mul_f32_e32 v22, v22, v15
	v_fma_f32 v21, v21, v14, v14
	v_mul_f32_e32 v20, 0x3f4c422a, v20
	v_add_f32_e32 v19, v19, v19
	v_mul_f32_e32 v6, 0xbfb8aa3b, v6
	v_and_b32_e32 v17, 0xffff0000, v17
	v_mul_f32_e32 v24, 0x3d372713, v18
	v_mul_f32_e32 v23, v23, v16
	v_fma_f32 v22, v22, v15, v15
	v_mul_f32_e32 v21, 0x3f4c422a, v21
	v_add_f32_e32 v20, v20, v20
	v_mul_f32_e32 v19, 0xbfb8aa3b, v19
	v_exp_f32_e32 v6, v6
	v_mul_f32_e32 v25, 0x3d372713, v17
	v_mul_f32_e32 v24, v24, v18
	v_fma_f32 v23, v23, v16, v16
	v_mul_f32_e32 v22, 0x3f4c422a, v22
	v_add_f32_e32 v21, v21, v21
	v_mul_f32_e32 v20, 0xbfb8aa3b, v20
	v_exp_f32_e32 v19, v19
	v_mul_f32_e32 v25, v25, v17
	v_fma_f32 v24, v24, v18, v18
	v_mul_f32_e32 v23, 0x3f4c422a, v23
	v_add_f32_e32 v22, v22, v22
	v_mul_f32_e32 v21, 0xbfb8aa3b, v21
	v_exp_f32_e32 v20, v20
	v_fma_f32 v25, v25, v17, v17
	v_mul_f32_e32 v24, 0x3f4c422a, v24
	v_add_f32_e32 v23, v23, v23
	v_mul_f32_e32 v22, 0xbfb8aa3b, v22
	v_exp_f32_e32 v21, v21
	v_mul_f32_e32 v25, 0x3f4c422a, v25
	v_add_f32_e32 v24, v24, v24
	v_mul_f32_e32 v23, 0xbfb8aa3b, v23
	v_exp_f32_e32 v22, v22
	v_add_f32_e32 v6, 1.0, v6
	v_add_f32_e32 v25, v25, v25
	v_mul_f32_e32 v24, 0xbfb8aa3b, v24
	v_exp_f32_e32 v23, v23
	v_add_f32_e32 v19, 1.0, v19
	v_rcp_f32_e32 v26, v6
	v_mul_f32_e32 v25, 0xbfb8aa3b, v25
	v_exp_f32_e32 v24, v24
	v_add_f32_e32 v20, 1.0, v20
	v_rcp_f32_e32 v19, v19
	v_exp_f32_e32 v25, v25
	v_add_f32_e32 v21, 1.0, v21
	v_rcp_f32_e32 v20, v20
	v_add_f32_e32 v22, 1.0, v22
	v_rcp_f32_e32 v21, v21
	v_add_f32_e32 v23, 1.0, v23
	v_rcp_f32_e32 v22, v22
	v_fma_f32 v6, v26, v0, 0
	v_add_f32_e32 v24, 1.0, v24
	v_rcp_f32_e32 v23, v23
	v_fmac_f32_e32 v6, v19, v7
	v_add_f32_e32 v25, 1.0, v25
	v_rcp_f32_e32 v24, v24
	v_fmac_f32_e32 v6, v20, v13
	v_rcp_f32_e32 v25, v25
	v_fmac_f32_e32 v6, v21, v14
	v_fmac_f32_e32 v6, v22, v15
	v_fmac_f32_e32 v6, v23, v16
	v_fmac_f32_e32 v6, v24, v18
	v_fmac_f32_e32 v6, v25, v17
	ds_bpermute_b32 v27, v3, v6
	s_waitcnt lgkmcnt(0)
	v_add_f32_e32 v6, v6, v27
	ds_bpermute_b32 v27, v8, v6
	s_waitcnt lgkmcnt(0)
	v_add_f32_e32 v6, v6, v27
	ds_bpermute_b32 v27, v9, v6
	s_waitcnt lgkmcnt(0)
	v_add_f32_e32 v6, v6, v27
	ds_bpermute_b32 v27, v10, v6
	s_waitcnt lgkmcnt(0)
	v_add_f32_e32 v6, v6, v27
	ds_bpermute_b32 v27, v11, v6
	s_waitcnt lgkmcnt(0)
	v_add_f32_e32 v6, v6, v27
	ds_bpermute_b32 v27, v12, v6
	s_waitcnt lgkmcnt(0)
	v_add_f32_e32 v6, v6, v27
	v_mul_f32_e32 v6, 0x3b000000, v6
	v_fma_f32 v7, v19, v7, -v6
	v_fma_f32 v0, v26, v0, -v6
	v_mul_f32_e32 v7, v7, v7
	v_fma_f32 v13, v20, v13, -v6
	v_fmac_f32_e32 v7, v0, v0
	v_fma_f32 v14, v21, v14, -v6
	v_fmac_f32_e32 v7, v13, v13
	v_fma_f32 v15, v22, v15, -v6
	v_fmac_f32_e32 v7, v14, v14
	v_fma_f32 v16, v23, v16, -v6
	v_fmac_f32_e32 v7, v15, v15
	v_fma_f32 v18, v24, v18, -v6
	v_fmac_f32_e32 v7, v16, v16
	v_fmac_f32_e32 v7, v18, v18
	v_fma_f32 v0, v25, v17, -v6
	v_fmac_f32_e32 v7, v0, v0
	ds_bpermute_b32 v0, v3, v7
	s_waitcnt lgkmcnt(0)
	v_add_f32_e32 v0, v7, v0
	ds_bpermute_b32 v7, v8, v0
	s_waitcnt lgkmcnt(0)
	v_add_f32_e32 v0, v0, v7
	ds_bpermute_b32 v7, v9, v0
	s_waitcnt lgkmcnt(0)
	v_add_f32_e32 v0, v0, v7
	ds_bpermute_b32 v7, v10, v0
	s_waitcnt lgkmcnt(0)
	v_add_f32_e32 v0, v0, v7
	ds_bpermute_b32 v7, v11, v0
	s_waitcnt lgkmcnt(0)
	v_add_f32_e32 v0, v0, v7
	ds_bpermute_b32 v7, v12, v0
	s_and_saveexec_b64 s[0:1], s[8:9]
	s_cbranch_execz .LBB0_359
	s_waitcnt lgkmcnt(0)
	v_add_f32_e32 v0, v0, v7
	v_fmamk_f32 v0, v0, 0x3b000000, v232
	v_mul_f32_e32 v7, 0x4f800000, v0
	v_cmp_gt_f32_e32 vcc, s80, v0
	s_add_i32 s5, s4, s3
	s_nop 0
	v_cndmask_b32_e32 v0, v0, v7, vcc
	v_sqrt_f32_e32 v7, v0
	s_nop 0
	v_add_u32_e32 v13, -1, v7
	v_fma_f32 v15, -v13, v7, v0
	v_add_u32_e32 v14, 1, v7
	v_cmp_ge_f32_e64 s[10:11], 0, v15
	s_nop 1
	v_cndmask_b32_e64 v13, v7, v13, s[10:11]
	v_fma_f32 v7, -v14, v7, v0
	v_cmp_lt_f32_e64 s[10:11], 0, v7
	s_nop 1
	v_cndmask_b32_e64 v7, v13, v14, s[10:11]
	v_mul_f32_e32 v13, 0x37800000, v7
	v_cndmask_b32_e32 v7, v7, v13, vcc
	v_cmp_class_f32_e32 vcc, v0, v231
	s_nop 1
	v_cndmask_b32_e32 v0, v7, v0, vcc
	v_div_scale_f32 v7, s[6:7], v0, v0, 1.0
	v_rcp_f32_e32 v13, v7
	s_nop 0
	v_fma_f32 v14, -v7, v13, 1.0
	v_fmac_f32_e32 v13, v14, v13
	v_div_scale_f32 v14, vcc, 1.0, v0, 1.0
	v_mul_f32_e32 v15, v14, v13
	v_fma_f32 v16, -v7, v15, v14
	v_fmac_f32_e32 v15, v16, v13
	v_fma_f32 v7, -v7, v15, v14
	v_div_fmas_f32 v7, v7, v13, v15
	v_div_fixup_f32 v7, v7, v0, 1.0
	v_mov_b32_e32 v0, s5
	ds_write_b64 v0, v[6:7]
	s_branch .LBB0_359

; #define LAS __attribute__((address_space(3)))
; __device__ __forceinline__ unsigned cvtpk(float lo, float hi) { f32x2_t v = {lo, hi}; bf16x2_t b = __builtin_convertvector(v, bf16x2_t); return __builtin_bit_cast(unsigned, b); }
; __device__ __forceinline__ float bflo(unsigned u) { return __uint_as_float(u << 16); }
; __device__ __forceinline__ float bfhi(unsigned u) { return __uint_as_float(u & 0xffff0000u); }
; __device__ __forceinline__ float geluf_(float x) { const float y = 0.7978845608028654f * (x + 0.044715f * x * x * x); return x * sigmoidf_(2.0f * y); }
; __device__ __forceinline__ void sgu_item(LAS unsigned char* lds, const bf16* PROJ, bf16* MIX, const float* lg, const float* lb, const float* ws_, const float* bs_, int item, int tid) {
;     ...
;         { const int s = tid & 127, cs = tid >> 7; const float mean = st[2 * s], rstd = st[2 * s + 1];
;           const bf16* vp = PROJ + (row0 + s) * NPROJ + 512 + 128 * g + 32 * cs;
; #pragma unroll
;           for (int q = 0; q < 4; ++q) { const u32x4 v = *(const u32x4*)(vp + 8 * q);
;               float x[8] = {bflo(v.x), bfhi(v.x), bflo(v.y), bfhi(v.y), bflo(v.z), bfhi(v.z), bflo(v.w), bfhi(v.w)};
; #pragma unroll
;               for (int e = 0; e < 8; ++e) { const int cl = 32 * cs + 8 * q + e; const int cgl = 128 * g + cl; const float y = (geluf_(x[e]) - mean) * rstd * lg[cgl] + lb[cgl];
;                   *(LAS unsigned short*)(vnT + cl * SGP + 2 * s) = (unsigned short)(cvtpk(y, 0.f) & 0xffffu); } } }
.LBB0_363:
	s_lshl_b32 s82, s1, 8
	v_lshl_add_u64 v[10:11], v[44:45], 0, s[82:83]
	ds_read_b64 v[54:55], v60
	global_load_dwordx4 v[2:5], v[10:11], off offset:1072
	global_load_dwordx4 v[6:9], v[10:11], off offset:1056
	global_load_dwordx4 v[26:29], v[10:11], off offset:1040
	s_nop 0
	global_load_dwordx4 v[10:13], v[10:11], off offset:1024
	s_lshl_b32 s2, s1, 7
	s_mov_b32 s3, 0
	s_waitcnt vmcnt(0)
	v_lshlrev_b32_e32 v14, 16, v10
	v_lshlrev_b32_e32 v71, 16, v11
	v_and_b32_e32 v72, 0xffff0000, v11
	v_mul_f32_e32 v11, 0x3d372713, v14
	v_mul_f32_e32 v11, v11, v14
	v_fma_f32 v11, v11, v14, v14
	v_mul_f32_e32 v11, 0x3f4c422a, v11
	v_add_f32_e32 v11, v11, v11
	v_mul_f32_e32 v11, 0xbfb8aa3b, v11
	v_exp_f32_e32 v11, v11
	v_and_b32_e32 v70, 0xffff0000, v10
	v_add_u32_e32 v10, s2, v42
	v_lshlrev_b32_e32 v73, 16, v12
	v_add_f32_e32 v11, 1.0, v11
	v_rcp_f32_e32 v11, v11
	v_and_b32_e32 v65, 0xffff0000, v12
	v_lshlrev_b32_e32 v64, 16, v13
	v_and_b32_e32 v0, 0xffff0000, v13
	s_waitcnt lgkmcnt(0)
	v_fma_f32 v11, v11, v14, -v54
	v_mul_f32_e32 v74, v55, v11
	v_ashrrev_i32_e32 v11, 31, v10
	v_lshlrev_b64 v[14:15], 2, v[10:11]
	v_lshl_add_u64 v[56:57], s[8:9], 0, v[14:15]
	v_lshl_add_u64 v[58:59], s[10:11], 0, v[14:15]
	global_load_dwordx4 v[10:13], v[56:57], off offset:48
	global_load_dwordx4 v[18:21], v[56:57], off offset:32
	global_load_dwordx4 v[30:33], v[56:57], off offset:16
	global_load_dwordx4 v[38:41], v[56:57], off
	global_load_dwordx4 v[14:17], v[58:59], off offset:48
	global_load_dwordx4 v[22:25], v[58:59], off offset:32
	global_load_dwordx4 v[34:37], v[58:59], off offset:16
	global_load_dwordx4 v[66:69], v[58:59], off
	s_waitcnt vmcnt(0)
	v_fma_f32 v38, v38, v74, v66
	v_cvt_pk_bf16_f32 v38, v38, s0
	ds_write_b16 v62, v38 offset:1024
	v_mul_f32_e32 v38, 0x3d372713, v70
	v_mul_f32_e32 v38, v38, v70
	v_fma_f32 v38, v38, v70, v70
	v_mul_f32_e32 v38, 0x3f4c422a, v38
	v_add_f32_e32 v38, v38, v38
	v_mul_f32_e32 v38, 0xbfb8aa3b, v38
	v_exp_f32_e32 v38, v38
	s_nop 0
	v_add_f32_e32 v38, 1.0, v38
	v_rcp_f32_e32 v38, v38
	s_nop 0
	v_fma_f32 v38, v38, v70, -v54
	v_mul_f32_e32 v38, v55, v38
	v_fma_f32 v38, v39, v38, v67
	v_cvt_pk_bf16_f32 v38, v38, s0
	ds_write_b16 v62, v38 offset:1296
	v_mul_f32_e32 v38, 0x3d372713, v71
	v_mul_f32_e32 v38, v38, v71
	v_fma_f32 v38, v38, v71, v71
	v_mul_f32_e32 v38, 0x3f4c422a, v38
	v_add_f32_e32 v38, v38, v38
	v_mul_f32_e32 v38, 0xbfb8aa3b, v38
	v_exp_f32_e32 v38, v38
	v_and_b32_e32 v39, 0xffff0000, v7
	v_add_f32_e32 v38, 1.0, v38
	v_rcp_f32_e32 v38, v38
	s_nop 0
	v_fma_f32 v38, v38, v71, -v54
	v_mul_f32_e32 v38, v55, v38
	v_fma_f32 v38, v40, v38, v68
	v_cvt_pk_bf16_f32 v38, v38, s0
	ds_write_b16 v62, v38 offset:1568
	v_mul_f32_e32 v38, 0x3d372713, v72
	v_mul_f32_e32 v38, v38, v72
	v_fma_f32 v38, v38, v72, v72
	v_mul_f32_e32 v38, 0x3f4c422a, v38
	v_add_f32_e32 v38, v38, v38
	v_mul_f32_e32 v38, 0xbfb8aa3b, v38
	v_exp_f32_e32 v38, v38
	v_lshlrev_b32_e32 v40, 16, v7
	v_add_f32_e32 v38, 1.0, v38
	v_rcp_f32_e32 v38, v38
	s_nop 0
	v_fma_f32 v38, v38, v72, -v54
	v_mul_f32_e32 v38, v55, v38
	v_fmac_f32_e32 v69, v41, v38
	v_cvt_pk_bf16_f32 v38, v69, s0
	ds_write_b16 v62, v38 offset:1840
	v_mul_f32_e32 v38, 0x3d372713, v73
	v_mul_f32_e32 v38, v38, v73
	v_fma_f32 v38, v38, v73, v73
	v_mul_f32_e32 v38, 0x3f4c422a, v38
	v_add_f32_e32 v38, v38, v38
	v_mul_f32_e32 v38, 0xbfb8aa3b, v38
	v_exp_f32_e32 v38, v38
	v_and_b32_e32 v41, 0xffff0000, v6
	v_add_f32_e32 v38, 1.0, v38
	v_rcp_f32_e32 v38, v38
	s_nop 0
	v_fma_f32 v38, v38, v73, -v54
	v_mul_f32_e32 v38, v55, v38
	v_fma_f32 v30, v30, v38, v34
	v_cvt_pk_bf16_f32 v30, v30, s0
	ds_write_b16 v62, v30 offset:2112
	v_mul_f32_e32 v30, 0x3d372713, v65
	v_mul_f32_e32 v30, v30, v65
	v_fma_f32 v30, v30, v65, v65
	v_mul_f32_e32 v30, 0x3f4c422a, v30
	v_add_f32_e32 v30, v30, v30
	v_mul_f32_e32 v30, 0xbfb8aa3b, v30
	v_exp_f32_e32 v30, v30
	v_lshlrev_b32_e32 v38, 16, v8
	v_add_f32_e32 v30, 1.0, v30
	v_rcp_f32_e32 v30, v30
	s_nop 0
	v_fma_f32 v30, v30, v65, -v54
	v_mul_f32_e32 v30, v55, v30
	v_fma_f32 v30, v31, v30, v35
	v_cvt_pk_bf16_f32 v30, v30, s0
	ds_write_b16 v62, v30 offset:2384
	v_mul_f32_e32 v30, 0x3d372713, v64
	v_mul_f32_e32 v30, v30, v64
	v_fma_f32 v30, v30, v64, v64
	v_mul_f32_e32 v30, 0x3f4c422a, v30
	v_add_f32_e32 v30, v30, v30
	v_mul_f32_e32 v30, 0xbfb8aa3b, v30
	v_exp_f32_e32 v30, v30
	v_lshlrev_b32_e32 v31, 16, v28
	v_and_b32_e32 v28, 0xffff0000, v28
	v_add_f32_e32 v30, 1.0, v30
	v_rcp_f32_e32 v30, v30
	s_nop 0
	v_fma_f32 v30, v30, v64, -v54
	v_mul_f32_e32 v30, v55, v30
	v_fma_f32 v30, v30, v32, v36
	v_cvt_pk_bf16_f32 v30, v30, s0
	ds_write_b16 v62, v30 offset:2656
	v_mul_f32_e32 v30, 0x3d372713, v0
	v_mul_f32_e32 v30, v30, v0
	v_fma_f32 v30, v30, v0, v0
	v_mul_f32_e32 v30, 0x3f4c422a, v30
	v_add_f32_e32 v30, v30, v30
	v_mul_f32_e32 v30, 0xbfb8aa3b, v30
	v_exp_f32_e32 v30, v30
	v_lshlrev_b32_e32 v32, 16, v29
	v_and_b32_e32 v29, 0xffff0000, v29
	v_add_f32_e32 v30, 1.0, v30
	v_rcp_f32_e32 v30, v30
	s_nop 0
	v_fma_f32 v0, v30, v0, -v54
	v_mul_f32_e32 v0, v55, v0
	v_fmac_f32_e32 v37, v0, v33
	v_cvt_pk_bf16_f32 v0, v37, s0
	ds_write_b16 v62, v0 offset:2928
	v_lshlrev_b32_e32 v0, 16, v26
	v_mul_f32_e32 v33, 0x3d372713, v0
	v_mul_f32_e32 v33, v33, v0
	v_fma_f32 v33, v33, v0, v0
	v_mul_f32_e32 v33, 0x3f4c422a, v33
	v_add_f32_e32 v33, v33, v33
	v_mul_f32_e32 v33, 0xbfb8aa3b, v33
	v_exp_f32_e32 v33, v33
	v_and_b32_e32 v26, 0xffff0000, v26
	v_lshlrev_b32_e32 v30, 16, v27
	v_and_b32_e32 v27, 0xffff0000, v27
	v_add_f32_e32 v33, 1.0, v33
	v_rcp_f32_e32 v33, v33
	v_and_b32_e32 v37, 0xffff0000, v8
	v_fma_f32 v0, v33, v0, -v54
	v_mul_f32_e32 v0, v55, v0
	v_fma_f32 v0, v18, v0, v22
	v_cvt_pk_bf16_f32 v0, v0, s0
; #define LAS __attribute__((address_space(3)))
; __device__ __forceinline__ unsigned cvtpk(float lo, float hi) { f32x2_t v = {lo, hi}; bf16x2_t b = __builtin_convertvector(v, bf16x2_t); return __builtin_bit_cast(unsigned, b); }
; __device__ __forceinline__ float bflo(unsigned u) { return __uint_as_float(u << 16); }
; __device__ __forceinline__ float bfhi(unsigned u) { return __uint_as_float(u & 0xffff0000u); }
; __device__ __forceinline__ float geluf_(float x) { const float y = 0.7978845608028654f * (x + 0.044715f * x * x * x); return x * sigmoidf_(2.0f * y); }
; __device__ __forceinline__ void sgu_item(LAS unsigned char* lds, const bf16* PROJ, bf16* MIX, const float* lg, const float* lb, const float* ws_, const float* bs_, int item, int tid) {
;     ...
;         { const int s = tid & 127, cs = tid >> 7; const float mean = st[2 * s], rstd = st[2 * s + 1];
;           const bf16* vp = PROJ + (row0 + s) * NPROJ + 512 + 128 * g + 32 * cs;
; #pragma unroll
;           for (int q = 0; q < 4; ++q) { const u32x4 v = *(const u32x4*)(vp + 8 * q);
;               float x[8] = {bflo(v.x), bfhi(v.x), bflo(v.y), bfhi(v.y), bflo(v.z), bfhi(v.z), bflo(v.w), bfhi(v.w)};
; #pragma unroll
;               for (int e = 0; e < 8; ++e) { const int cl = 32 * cs + 8 * q + e; const int cgl = 128 * g + cl; const float y = (geluf_(x[e]) - mean) * rstd * lg[cgl] + lb[cgl];
;                   *(LAS unsigned short*)(vnT + cl * SGP + 2 * s) = (unsigned short)(cvtpk(y, 0.f) & 0xffffu); } } }
	ds_write_b16 v62, v0 offset:3200
	v_mul_f32_e32 v0, 0x3d372713, v26
	v_mul_f32_e32 v0, v0, v26
	v_fma_f32 v0, v0, v26, v26
	v_mul_f32_e32 v0, 0x3f4c422a, v0
	v_add_f32_e32 v0, v0, v0
	v_mul_f32_e32 v0, 0xbfb8aa3b, v0
	v_exp_f32_e32 v0, v0
	v_lshlrev_b32_e32 v33, 16, v9
	v_add_f32_e32 v0, 1.0, v0
	v_rcp_f32_e32 v0, v0
	s_nop 0
	v_fma_f32 v0, v0, v26, -v54
	v_mul_f32_e32 v0, v55, v0
	v_fma_f32 v0, v19, v0, v23
	v_cvt_pk_bf16_f32 v0, v0, s0
	ds_write_b16 v62, v0 offset:3472
	v_mul_f32_e32 v0, 0x3d372713, v30
	v_mul_f32_e32 v0, v0, v30
	v_fma_f32 v0, v0, v30, v30
	v_mul_f32_e32 v0, 0x3f4c422a, v0
	v_add_f32_e32 v0, v0, v0
	v_mul_f32_e32 v0, 0xbfb8aa3b, v0
	v_exp_f32_e32 v0, v0
	s_nop 0
	v_add_f32_e32 v0, 1.0, v0
	v_rcp_f32_e32 v0, v0
	s_nop 0
	v_fma_f32 v0, v0, v30, -v54
	v_mul_f32_e32 v0, v55, v0
	v_fma_f32 v0, v20, v0, v24
	v_cvt_pk_bf16_f32 v0, v0, s0
	ds_write_b16 v62, v0 offset:3744
	v_mul_f32_e32 v0, 0x3d372713, v27
	v_mul_f32_e32 v0, v0, v27
	v_fma_f32 v0, v0, v27, v27
	v_mul_f32_e32 v0, 0x3f4c422a, v0
	v_add_f32_e32 v0, v0, v0
	v_mul_f32_e32 v0, 0xbfb8aa3b, v0
	v_exp_f32_e32 v0, v0
	s_nop 0
	v_add_f32_e32 v0, 1.0, v0
	v_rcp_f32_e32 v0, v0
	s_nop 0
	v_fma_f32 v0, v0, v27, -v54
	v_mul_f32_e32 v0, v55, v0
	v_fmac_f32_e32 v25, v21, v0
	v_cvt_pk_bf16_f32 v0, v25, s0
	ds_write_b16 v62, v0 offset:4016
	v_mul_f32_e32 v0, 0x3d372713, v31
	v_mul_f32_e32 v0, v0, v31
	v_fma_f32 v0, v0, v31, v31
	v_mul_f32_e32 v0, 0x3f4c422a, v0
	v_add_f32_e32 v0, v0, v0
	v_mul_f32_e32 v0, 0xbfb8aa3b, v0
	v_exp_f32_e32 v0, v0
	s_nop 0
	v_add_f32_e32 v0, 1.0, v0
	v_rcp_f32_e32 v0, v0
	s_nop 0
	v_fma_f32 v0, v0, v31, -v54
	v_mul_f32_e32 v0, v55, v0
	v_fma_f32 v0, v10, v0, v14
	v_cvt_pk_bf16_f32 v0, v0, s0
	ds_write_b16 v62, v0 offset:4288
	v_mul_f32_e32 v0, 0x3d372713, v28
	v_mul_f32_e32 v0, v0, v28
	v_fma_f32 v0, v0, v28, v28
	v_mul_f32_e32 v0, 0x3f4c422a, v0
	v_add_f32_e32 v0, v0, v0
	v_mul_f32_e32 v0, 0xbfb8aa3b, v0
	v_exp_f32_e32 v0, v0
	v_lshlrev_b32_e32 v10, 16, v6
	v_mul_f32_e32 v6, 0x3d372713, v10
	v_mul_f32_e32 v6, v6, v10
	v_add_f32_e32 v0, 1.0, v0
	v_rcp_f32_e32 v0, v0
	v_fma_f32 v6, v6, v10, v10
	v_mul_f32_e32 v6, 0x3f4c422a, v6
	v_add_f32_e32 v6, v6, v6
	v_fma_f32 v0, v0, v28, -v54
	v_mul_f32_e32 v0, v55, v0
	v_fma_f32 v0, v11, v0, v15
	v_cvt_pk_bf16_f32 v0, v0, s0
	ds_write_b16 v62, v0 offset:4560
	v_mul_f32_e32 v0, 0x3d372713, v32
	v_mul_f32_e32 v0, v0, v32
	v_fma_f32 v0, v0, v32, v32
	v_mul_f32_e32 v0, 0x3f4c422a, v0
	v_add_f32_e32 v0, v0, v0
	v_mul_f32_e32 v0, 0xbfb8aa3b, v0
	v_exp_f32_e32 v0, v0
	v_mul_f32_e32 v6, 0xbfb8aa3b, v6
	v_exp_f32_e32 v6, v6
	v_add_f32_e32 v0, 1.0, v0
	v_rcp_f32_e32 v0, v0
	v_add_f32_e32 v6, 1.0, v6
	v_rcp_f32_e32 v6, v6
	v_fma_f32 v0, v0, v32, -v54
	v_mul_f32_e32 v0, v55, v0
	v_fma_f32 v0, v0, v12, v16
	v_cvt_pk_bf16_f32 v0, v0, s0
	ds_write_b16 v62, v0 offset:4832
	v_mul_f32_e32 v0, 0x3d372713, v29
	v_mul_f32_e32 v0, v0, v29
	v_fma_f32 v0, v0, v29, v29
	v_mul_f32_e32 v0, 0x3f4c422a, v0
	v_add_f32_e32 v0, v0, v0
	v_mul_f32_e32 v0, 0xbfb8aa3b, v0
	v_exp_f32_e32 v0, v0
	v_fma_f32 v6, v6, v10, -v54
	v_mul_f32_e32 v64, v55, v6
	v_add_f32_e32 v0, 1.0, v0
	v_rcp_f32_e32 v0, v0
	s_nop 0
	v_fma_f32 v0, v0, v29, -v54
	v_mul_f32_e32 v0, v55, v0
	v_fmac_f32_e32 v17, v0, v13
	v_cvt_pk_bf16_f32 v0, v17, s0
	ds_write_b16 v62, v0 offset:5104
	v_and_b32_e32 v0, 0xffff0000, v9
	global_load_dwordx3 v[30:32], v[56:57], off offset:112
	global_load_dwordx4 v[6:9], v[56:57], off offset:96
	global_load_dwordx4 v[14:17], v[56:57], off offset:80
	global_load_dwordx4 v[22:25], v[56:57], off offset:64
	global_load_dwordx3 v[34:36], v[58:59], off offset:112
	global_load_dwordx4 v[10:13], v[58:59], off offset:96
	global_load_dwordx4 v[18:21], v[58:59], off offset:80
	global_load_dwordx4 v[26:29], v[58:59], off offset:64
	s_waitcnt vmcnt(0)
	v_fma_f32 v22, v22, v64, v26
	v_cvt_pk_bf16_f32 v22, v22, s0
	ds_write_b16 v62, v22 offset:5376
	v_mul_f32_e32 v22, 0x3d372713, v41
	v_mul_f32_e32 v22, v22, v41
	v_fma_f32 v22, v22, v41, v41
	v_mul_f32_e32 v22, 0x3f4c422a, v22
	v_add_f32_e32 v22, v22, v22
	v_mul_f32_e32 v22, 0xbfb8aa3b, v22
	v_exp_f32_e32 v22, v22
	s_nop 0
	v_add_f32_e32 v22, 1.0, v22
	v_rcp_f32_e32 v22, v22
	s_nop 0
	v_fma_f32 v22, v22, v41, -v54
	v_mul_f32_e32 v22, v55, v22
	v_fma_f32 v22, v23, v22, v27
	v_cvt_pk_bf16_f32 v22, v22, s0
	ds_write_b16 v62, v22 offset:5648
	v_mul_f32_e32 v22, 0x3d372713, v40
	v_mul_f32_e32 v22, v22, v40
	v_fma_f32 v22, v22, v40, v40
	v_mul_f32_e32 v22, 0x3f4c422a, v22
	v_add_f32_e32 v22, v22, v22
	v_mul_f32_e32 v22, 0xbfb8aa3b, v22
	v_exp_f32_e32 v22, v22
	s_nop 0
	v_add_f32_e32 v22, 1.0, v22
	v_rcp_f32_e32 v22, v22
	s_nop 0
	v_fma_f32 v22, v22, v40, -v54
	v_mul_f32_e32 v22, v55, v22
	v_fma_f32 v22, v24, v22, v28
	v_cvt_pk_bf16_f32 v22, v22, s0
	ds_write_b16 v62, v22 offset:5920
	v_mul_f32_e32 v22, 0x3d372713, v39
	v_mul_f32_e32 v22, v22, v39
	v_fma_f32 v22, v22, v39, v39
	v_mul_f32_e32 v22, 0x3f4c422a, v22
	v_add_f32_e32 v22, v22, v22
	v_mul_f32_e32 v22, 0xbfb8aa3b, v22
	v_exp_f32_e32 v22, v22
	s_nop 0
	v_add_f32_e32 v22, 1.0, v22
	v_rcp_f32_e32 v22, v22
	s_nop 0
	v_fma_f32 v22, v22, v39, -v54
	v_mul_f32_e32 v22, v55, v22
	v_fmac_f32_e32 v29, v25, v22
	v_cvt_pk_bf16_f32 v22, v29, s0
	ds_write_b16 v62, v22 offset:6192
	v_mul_f32_e32 v22, 0x3d372713, v38
	v_mul_f32_e32 v22, v22, v38
	v_fma_f32 v22, v22, v38, v38
	v_mul_f32_e32 v22, 0x3f4c422a, v22
	v_add_f32_e32 v22, v22, v22
	v_mul_f32_e32 v22, 0xbfb8aa3b, v22
	v_exp_f32_e32 v22, v22
	s_nop 0
	v_add_f32_e32 v22, 1.0, v22
	v_rcp_f32_e32 v22, v22
	s_nop 0
	v_fma_f32 v22, v22, v38, -v54
	v_mul_f32_e32 v22, v55, v22
	v_fma_f32 v14, v14, v22, v18
	v_cvt_pk_bf16_f32 v14, v14, s0
; #define LAS __attribute__((address_space(3)))
; __device__ __forceinline__ unsigned cvtpk(float lo, float hi) { f32x2_t v = {lo, hi}; bf16x2_t b = __builtin_convertvector(v, bf16x2_t); return __builtin_bit_cast(unsigned, b); }
; __device__ __forceinline__ float bflo(unsigned u) { return __uint_as_float(u << 16); }
; __device__ __forceinline__ float bfhi(unsigned u) { return __uint_as_float(u & 0xffff0000u); }
; __device__ __forceinline__ float geluf_(float x) { const float y = 0.7978845608028654f * (x + 0.044715f * x * x * x); return x * sigmoidf_(2.0f * y); }
; __device__ __forceinline__ void sgu_item(LAS unsigned char* lds, const bf16* PROJ, bf16* MIX, const float* lg, const float* lb, const float* ws_, const float* bs_, int item, int tid) {
;     ...
;           for (int q = 0; q < 4; ++q) { const u32x4 v = *(const u32x4*)(vp + 8 * q);
;               float x[8] = {bflo(v.x), bfhi(v.x), bflo(v.y), bfhi(v.y), bflo(v.z), bfhi(v.z), bflo(v.w), bfhi(v.w)};
; #pragma unroll
;               for (int e = 0; e < 8; ++e) { const int cl = 32 * cs + 8 * q + e; const int cgl = 128 * g + cl; const float y = (geluf_(x[e]) - mean) * rstd * lg[cgl] + lb[cgl];
;                   *(LAS unsigned short*)(vnT + cl * SGP + 2 * s) = (unsigned short)(cvtpk(y, 0.f) & 0xffffu); } } }
;         __syncthreads();
;         f32x16 acc[2];
; #pragma unroll
;         for (int r = 0; r < 16; ++r) { acc[0][r] = 0.f; acc[1][r] = 0.f; }
;         const int trow = 32 * wt + r32; const float* wrow = ws_ + ((size_t)g * 128 + trow) * 128;
;         for (int ks = 0; ks < 2 * (wt + 1); ++ks) { const int s0 = 16 * ks + 8 * hi;
;             const f32x4 w0 = *(const f32x4*)(wrow + s0), w1 = *(const f32x4*)(wrow + s0 + 4);
	ds_write_b16 v62, v14 offset:6464
	v_mul_f32_e32 v14, 0x3d372713, v37
	v_mul_f32_e32 v14, v14, v37
	v_fma_f32 v14, v14, v37, v37
	v_mul_f32_e32 v14, 0x3f4c422a, v14
	v_add_f32_e32 v14, v14, v14
	v_mul_f32_e32 v14, 0xbfb8aa3b, v14
	v_exp_f32_e32 v14, v14
	v_mov_b32_e32 v18, 0
	v_mov_b64_e32 v[38:39], v[52:53]
	v_mov_b32_e32 v22, v18
	v_add_f32_e32 v14, 1.0, v14
	v_rcp_f32_e32 v14, v14
	v_mov_b32_e32 v23, v18
	v_mov_b32_e32 v24, v18
	v_mov_b32_e32 v25, v18
	v_fma_f32 v14, v14, v37, -v54
	v_mul_f32_e32 v14, v55, v14
	v_fma_f32 v14, v15, v14, v19
	v_cvt_pk_bf16_f32 v14, v14, s0
	ds_write_b16 v62, v14 offset:6736
	v_mul_f32_e32 v14, 0x3d372713, v33
	v_mul_f32_e32 v14, v14, v33
	v_fma_f32 v14, v14, v33, v33
	v_mul_f32_e32 v14, 0x3f4c422a, v14
	v_add_f32_e32 v14, v14, v14
	v_mul_f32_e32 v14, 0xbfb8aa3b, v14
	v_exp_f32_e32 v14, v14
	v_lshlrev_b32_e32 v15, 16, v4
	v_and_b32_e32 v4, 0xffff0000, v4
	v_mov_b32_e32 v19, v18
	v_add_f32_e32 v14, 1.0, v14
	v_rcp_f32_e32 v14, v14
	v_mov_b32_e32 v26, v18
	v_mov_b32_e32 v27, v18
	v_mov_b32_e32 v28, v18
	v_fma_f32 v14, v14, v33, -v54
	v_mul_f32_e32 v14, v55, v14
	v_fma_f32 v14, v14, v16, v20
	v_cvt_pk_bf16_f32 v14, v14, s0
	ds_write_b16 v62, v14 offset:7008
	v_mul_f32_e32 v14, 0x3d372713, v0
	v_mul_f32_e32 v14, v14, v0
	v_fma_f32 v14, v14, v0, v0
	v_mul_f32_e32 v14, 0x3f4c422a, v14
	v_add_f32_e32 v14, v14, v14
	v_mul_f32_e32 v14, 0xbfb8aa3b, v14
	v_exp_f32_e32 v14, v14
	v_lshlrev_b32_e32 v16, 16, v5
	v_and_b32_e32 v5, 0xffff0000, v5
	v_mov_b32_e32 v20, v18
	v_add_f32_e32 v14, 1.0, v14
	v_rcp_f32_e32 v14, v14
	v_mov_b32_e32 v29, v18
	v_mov_b32_e32 v33, v18
	v_fma_f32 v0, v14, v0, -v54
	v_mul_f32_e32 v0, v55, v0
	v_fmac_f32_e32 v21, v0, v17
	v_cvt_pk_bf16_f32 v0, v21, s0
	ds_write_b16 v62, v0 offset:7280
	v_lshlrev_b32_e32 v0, 16, v2
	v_mul_f32_e32 v17, 0x3d372713, v0
	v_mul_f32_e32 v17, v17, v0
	v_fma_f32 v17, v17, v0, v0
	v_mul_f32_e32 v17, 0x3f4c422a, v17
	v_add_f32_e32 v17, v17, v17
	v_mul_f32_e32 v17, 0xbfb8aa3b, v17
	v_exp_f32_e32 v17, v17
	v_and_b32_e32 v2, 0xffff0000, v2
	v_lshlrev_b32_e32 v14, 16, v3
	v_and_b32_e32 v3, 0xffff0000, v3
	v_add_f32_e32 v17, 1.0, v17
	v_rcp_f32_e32 v17, v17
	v_mov_b32_e32 v21, v18
	v_fma_f32 v0, v17, v0, -v54
	v_mul_f32_e32 v0, v55, v0
	v_fma_f32 v0, v6, v0, v10
	v_cvt_pk_bf16_f32 v0, v0, s0
	ds_write_b16 v62, v0 offset:7552
	v_mul_f32_e32 v0, 0x3d372713, v2
	v_mul_f32_e32 v0, v0, v2
	v_fma_f32 v0, v0, v2, v2
	v_mul_f32_e32 v0, 0x3f4c422a, v0
	v_add_f32_e32 v0, v0, v0
	v_mul_f32_e32 v0, 0xbfb8aa3b, v0
	v_exp_f32_e32 v0, v0
	v_mov_b32_e32 v6, v18
	v_mov_b32_e32 v10, v18
	v_mov_b32_e32 v17, v18
	v_add_f32_e32 v0, 1.0, v0
	v_rcp_f32_e32 v0, v0
	s_nop 0
	v_fma_f32 v0, v0, v2, -v54
	v_mul_f32_e32 v0, v55, v0
	v_fma_f32 v0, v7, v0, v11
	v_cvt_pk_bf16_f32 v0, v0, s0
	ds_write_b16 v62, v0 offset:7824
	v_mul_f32_e32 v0, 0x3d372713, v14
	v_mul_f32_e32 v0, v0, v14
	v_fma_f32 v0, v0, v14, v14
	v_mul_f32_e32 v0, 0x3f4c422a, v0
	v_add_f32_e32 v0, v0, v0
	v_mul_f32_e32 v0, 0xbfb8aa3b, v0
	v_exp_f32_e32 v0, v0
	v_add_u32_e32 v2, s2, v47
	v_mov_b32_e32 v7, v18
	v_mov_b32_e32 v11, v18
	v_add_f32_e32 v0, 1.0, v0
	v_rcp_f32_e32 v0, v0
	s_nop 0
	v_fma_f32 v0, v0, v14, -v54
	v_mul_f32_e32 v0, v55, v0
	v_fma_f32 v0, v8, v0, v12
	v_cvt_pk_bf16_f32 v0, v0, s0
	ds_write_b16 v62, v0 offset:8096
	v_mul_f32_e32 v0, 0x3d372713, v3
	v_mul_f32_e32 v0, v0, v3
	v_fma_f32 v0, v0, v3, v3
	v_mul_f32_e32 v0, 0x3f4c422a, v0
	v_add_f32_e32 v0, v0, v0
	v_mul_f32_e32 v0, 0xbfb8aa3b, v0
	v_exp_f32_e32 v0, v0
	v_mov_b32_e32 v8, v18
	v_mov_b32_e32 v12, v18
	v_mov_b32_e32 v14, v18
	v_add_f32_e32 v0, 1.0, v0
	v_rcp_f32_e32 v0, v0
	s_nop 0
	v_fma_f32 v0, v0, v3, -v54
	v_mul_f32_e32 v0, v55, v0
	v_fmac_f32_e32 v13, v9, v0
	v_cvt_pk_bf16_f32 v0, v13, s0
	ds_write_b16 v62, v0 offset:8368
	v_mul_f32_e32 v0, 0x3d372713, v15
	v_mul_f32_e32 v0, v0, v15
	v_fma_f32 v0, v0, v15, v15
	v_mul_f32_e32 v0, 0x3f4c422a, v0
	v_add_f32_e32 v0, v0, v0
	v_mul_f32_e32 v0, 0xbfb8aa3b, v0
	v_exp_f32_e32 v0, v0
	v_ashrrev_i32_e32 v3, 31, v2
	v_lshlrev_b64 v[2:3], 2, v[2:3]
	v_mov_b32_e32 v9, v18
	v_add_f32_e32 v0, 1.0, v0
	v_rcp_f32_e32 v0, v0
	v_mov_b32_e32 v13, v18
	v_fma_f32 v0, v0, v15, -v54
	v_mul_f32_e32 v0, v55, v0
	v_fma_f32 v0, v30, v0, v34
	v_cvt_pk_bf16_f32 v0, v0, s0
	ds_write_b16 v62, v0 offset:8640
	v_mul_f32_e32 v0, 0x3d372713, v4
	v_mul_f32_e32 v0, v0, v4
	v_fma_f32 v0, v0, v4, v4
	v_mul_f32_e32 v0, 0x3f4c422a, v0
	v_add_f32_e32 v0, v0, v0
	v_mul_f32_e32 v0, 0xbfb8aa3b, v0
	v_exp_f32_e32 v0, v0
	v_mov_b32_e32 v30, v18
	v_mov_b32_e32 v15, v18
	v_add_f32_e32 v0, 1.0, v0
	v_rcp_f32_e32 v0, v0
	s_nop 0
	v_fma_f32 v0, v0, v4, -v54
	v_mul_f32_e32 v0, v55, v0
	v_fma_f32 v0, v31, v0, v35
	v_cvt_pk_bf16_f32 v0, v0, s0
	ds_write_b16 v62, v0 offset:8912
	v_mul_f32_e32 v0, 0x3d372713, v16
	v_mul_f32_e32 v0, v0, v16
	v_fma_f32 v0, v0, v16, v16
	v_mul_f32_e32 v0, 0x3f4c422a, v0
	v_add_f32_e32 v0, v0, v0
	v_mul_f32_e32 v0, 0xbfb8aa3b, v0
	v_exp_f32_e32 v0, v0
	v_mov_b32_e32 v31, v18
	v_add_f32_e32 v0, 1.0, v0
	v_rcp_f32_e32 v0, v0
	s_nop 0
	v_fma_f32 v0, v0, v16, -v54
	v_mul_f32_e32 v0, v55, v0
	v_fmac_f32_e32 v36, v0, v32
	v_cvt_pk_bf16_f32 v0, v36, s0
	ds_write_b16 v62, v0 offset:9184
	v_mul_f32_e32 v0, 0x3d372713, v5
	v_mul_f32_e32 v0, v0, v5
	v_fma_f32 v0, v0, v5, v5
	v_mul_f32_e32 v0, 0x3f4c422a, v0
	v_add_f32_e32 v0, v0, v0
	v_mul_f32_e32 v0, 0xbfb8aa3b, v0
	v_exp_f32_e32 v0, v0
	v_mov_b32_e32 v32, v18
	v_mov_b32_e32 v16, v18
	v_add_f32_e32 v0, 1.0, v0
	v_rcp_f32_e32 v0, v0
	s_nop 0
	v_fma_f32 v0, v0, v5, -v54
	v_lshl_add_u64 v[4:5], s[8:9], 0, v[2:3]
	v_lshl_add_u64 v[2:3], s[10:11], 0, v[2:3]
	global_load_dword v4, v[4:5], off
	v_mul_f32_e32 v0, v55, v0
	global_load_dword v2, v[2:3], off
	v_mov_b32_e32 v3, v18
	v_mov_b32_e32 v5, v18
	s_waitcnt vmcnt(0)
	v_fmac_f32_e32 v2, v0, v4
	v_cvt_pk_bf16_f32 v0, v2, s0
	ds_write_b16 v63, v0 offset:1024
	v_mov_b32_e32 v0, v61
	v_mov_b32_e32 v2, v18
	v_mov_b32_e32 v4, v18
	s_waitcnt lgkmcnt(0)
	s_barrier
	global_load_dwordx4 v[100:103], v[38:39], off
	global_load_dwordx4 v[104:107], v[38:39], off offset:-16
; #define LAS __attribute__((address_space(3)))
; __device__ __forceinline__ unsigned cvtpk(float lo, float hi) { f32x2_t v = {lo, hi}; bf16x2_t b = __builtin_convertvector(v, bf16x2_t); return __builtin_bit_cast(unsigned, b); }
; __device__ __forceinline__ float bflo(unsigned u) { return __uint_as_float(u << 16); }
; __device__ __forceinline__ float bfhi(unsigned u) { return __uint_as_float(u & 0xffff0000u); }
; __device__ __forceinline__ float geluf_(float x) { const float y = 0.7978845608028654f * (x + 0.044715f * x * x * x); return x * sigmoidf_(2.0f * y); }
; __device__ __forceinline__ void sgu_item(LAS unsigned char* lds, const bf16* PROJ, bf16* MIX, const float* lg, const float* lb, const float* ws_, const float* bs_, int item, int tid) {
;     ...
;         const int trow = 32 * wt + r32; const float* wrow = ws_ + ((size_t)g * 128 + trow) * 128;
;         for (int ks = 0; ks < 2 * (wt + 1); ++ks) { const int s0 = 16 * ks + 8 * hi;
;             const f32x4 w0 = *(const f32x4*)(wrow + s0), w1 = *(const f32x4*)(wrow + s0 + 4);
;             u32x4 pk; pk.x = cvtpk(s0 + 0 <= trow ? w0.x : 0.f, s0 + 1 <= trow ? w0.y : 0.f); pk.y = cvtpk(s0 + 2 <= trow ? w0.z : 0.f, s0 + 3 <= trow ? w0.w : 0.f);
;             pk.z = cvtpk(s0 + 4 <= trow ? w1.x : 0.f, s0 + 5 <= trow ? w1.y : 0.f); pk.w = cvtpk(s0 + 6 <= trow ? w1.z : 0.f, s0 + 7 <= trow ? w1.w : 0.f);
;             const bf16x8 wa = __builtin_bit_cast(bf16x8, pk);
; #pragma unroll
;             for (int ct = 0; ct < 2; ++ct) { const bf16x8 vb = *(LAS const bf16x8*)(vnT + (64 * wcg + 32 * ct + r32) * SGP + s0 * 2); acc[ct] = MFMA32(vb, wa, acc[ct]); } }
;         { const int t = 32 * wt + r32; const float bias = bs_[g * 128 + t]; const bf16* up = PROJ + (row0 + t) * NPROJ + 128 * g + 64 * wcg + 4 * hi; bf16* op = MIX + (row0 + t) * D + 128 * g + 64 * wcg + 4 * hi;
; #pragma unroll
;           for (int ct = 0; ct < 2; ++ct)
; #pragma unroll
;             for (int g4 = 0; g4 < 4; ++g4) { const u32x2 uw = *(const u32x2*)(up + 32 * ct + 8 * g4);
;                 const float o0 = geluf_(bflo(uw.x)) * (acc[ct][4 * g4] + bias), o1 = geluf_(bfhi(uw.x)) * (acc[ct][4 * g4 + 1] + bias), o2 = geluf_(bflo(uw.y)) * (acc[ct][4 * g4 + 2] + bias), o3 = geluf_(bfhi(uw.y)) * (acc[ct][4 * g4 + 3] + bias);
;                 u32x2 w; w.x = cvtpk(o0, o1); w.y = cvtpk(o2, o3); *(u32x2*)(op + 32 * ct + 8 * g4) = w; } }
.LBB0_364:
	v_add_u32_e32 v40, s3, v46
	v_cmp_le_u32_e32 vcc, v40, v43
	s_add_i32 s3, s3, 16
	v_lshl_add_u64 v[38:39], v[38:39], 0, 64
	s_cmp_eq_u32 s0, s3
	s_waitcnt vmcnt(0)
	v_mov_b32_e32 v54, v100
	v_mov_b32_e32 v55, v101
	v_mov_b32_e32 v56, v102
	v_mov_b32_e32 v57, v103
	v_mov_b32_e32 v34, v104
	v_mov_b32_e32 v35, v105
	v_mov_b32_e32 v36, v106
	v_mov_b32_e32 v37, v107
	s_cbranch_scc1 .Lsgu_c_nopf
	global_load_dwordx4 v[100:103], v[38:39], off
	global_load_dwordx4 v[104:107], v[38:39], off offset:-16
.Lsgu_c_nopf:
	v_cndmask_b32_e32 v34, 0, v34, vcc
	v_cmp_lt_u32_e32 vcc, v40, v43
	s_nop 1
	v_cndmask_b32_e32 v35, 0, v35, vcc
	v_cvt_pk_bf16_f32 v34, v34, v35
	v_add_u32_e32 v35, 2, v40
	v_cmp_le_u32_e32 vcc, v35, v43
	s_nop 1
	v_cndmask_b32_e32 v35, 0, v36, vcc
	v_add_u32_e32 v36, 3, v40
	v_cmp_le_u32_e32 vcc, v36, v43
	s_nop 1
	v_cndmask_b32_e32 v36, 0, v37, vcc
	v_cvt_pk_bf16_f32 v35, v35, v36
	v_add_u32_e32 v36, 4, v40
	v_cmp_le_u32_e32 vcc, v36, v43
	v_add_u32_e32 v37, 5, v40
	s_nop 0
	v_cndmask_b32_e32 v36, 0, v54, vcc
	v_cmp_le_u32_e32 vcc, v37, v43
	s_nop 1
	v_cndmask_b32_e32 v37, 0, v55, vcc
	v_cvt_pk_bf16_f32 v36, v36, v37
	v_add_u32_e32 v37, 6, v40
	v_cmp_le_u32_e32 vcc, v37, v43
	v_add_u32_e32 v40, 7, v40
	s_nop 0
	v_cndmask_b32_e32 v37, 0, v56, vcc
	v_cmp_le_u32_e32 vcc, v40, v43
	s_nop 1
	v_cndmask_b32_e32 v40, 0, v57, vcc
	ds_read_b128 v[54:57], v0
	v_cvt_pk_bf16_f32 v37, v37, v40
	s_waitcnt lgkmcnt(0)
	s_nop 0
	v_mfma_f32_32x32x16_bf16 v[18:33], v[54:57], v[34:37], v[18:33]
	ds_read_b128 v[54:57], v0 offset:8704
	v_add_u32_e32 v0, 32, v0
	s_waitcnt lgkmcnt(0)
	v_mfma_f32_32x32x16_bf16 v[2:17], v[54:57], v[34:37], v[2:17]
	s_cbranch_scc0 .LBB0_364
	s_lshl_b32 s82, s2, 1
	v_lshl_add_u64 v[36:37], v[48:49], 0, s[82:83]
	global_load_dwordx2 v[38:39], v[36:37], off
	v_or_b32_e32 v0, s2, v43
	v_lshl_add_u64 v[34:35], v[0:1], 2, s[14:15]
	global_load_dword v0, v[34:35], off
	v_lshl_add_u64 v[34:35], v[50:51], 0, s[82:83]
	s_add_i32 s1, s1, 1
	s_mov_b64 s[2:3], 0x10000
	v_lshl_add_u64 v[52:53], v[52:53], 0, s[2:3]
	s_cmp_eq_u32 s1, 4
	s_waitcnt vmcnt(1)
	v_lshlrev_b32_e32 v40, 16, v38
	v_and_b32_e32 v41, 0xffff0000, v38
	v_mul_f32_e32 v38, 0x3d372713, v40
	v_mul_f32_e32 v38, v38, v40
	v_mov_b32_e32 v54, v40
	v_fmac_f32_e32 v54, v38, v54
	v_mul_f32_e32 v38, 0x3f4c422a, v54
	v_add_f32_e32 v38, v38, v38
	v_mul_f32_e32 v38, 0xbfb8aa3b, v38
	v_exp_f32_e32 v38, v38
	v_mov_b32_e32 v55, v41
	s_waitcnt vmcnt(0)
	v_pk_add_f32 v[18:19], v[18:19], v[0:1] op_sel_hi:[1,0]
	v_pk_add_f32 v[20:21], v[20:21], v[0:1] op_sel_hi:[1,0]
	v_add_f32_e32 v38, 1.0, v38
	v_rcp_f32_e32 v54, v38
	v_mul_f32_e32 v38, 0x3d372713, v41
	v_mul_f32_e32 v38, v38, v41
	v_fmac_f32_e32 v55, v38, v55
	v_mul_f32_e32 v38, 0x3f4c422a, v55
	v_add_f32_e32 v38, v38, v38
	v_mul_f32_e32 v38, 0xbfb8aa3b, v38
	v_exp_f32_e32 v38, v38
	v_pk_add_f32 v[22:23], v[22:23], v[0:1] op_sel_hi:[1,0]
	v_pk_add_f32 v[2:3], v[2:3], v[0:1] op_sel_hi:[1,0]
	v_pk_add_f32 v[4:5], v[4:5], v[0:1] op_sel_hi:[1,0]
	v_add_f32_e32 v38, 1.0, v38
	v_rcp_f32_e32 v55, v38
	v_lshlrev_b32_e32 v38, 16, v39
	v_and_b32_e32 v39, 0xffff0000, v39
	v_pk_add_f32 v[6:7], v[6:7], v[0:1] op_sel_hi:[1,0]
	v_pk_mul_f32 v[40:41], v[54:55], v[40:41]
	v_mov_b32_e32 v54, v39
	v_pk_mul_f32 v[18:19], v[18:19], v[40:41]
	v_mul_f32_e32 v40, 0x3d372713, v38
	v_mul_f32_e32 v40, v40, v38
	v_mov_b32_e32 v41, v38
	v_fmac_f32_e32 v41, v40, v41
	v_mul_f32_e32 v40, 0x3f4c422a, v41
	v_mul_f32_e32 v41, 0x3d372713, v39
	v_mul_f32_e32 v41, v41, v39
	v_fmac_f32_e32 v54, v41, v54
	v_mul_f32_e32 v41, 0x3f4c422a, v54
	v_add_f32_e32 v40, v40, v40
	v_add_f32_e32 v41, v41, v41
	v_mul_f32_e32 v40, 0xbfb8aa3b, v40
	v_mul_f32_e32 v41, 0xbfb8aa3b, v41
	v_exp_f32_e32 v40, v40
	v_exp_f32_e32 v41, v41
	v_cvt_pk_bf16_f32 v18, v18, v19
	v_add_f32_e32 v40, 1.0, v40
	v_add_f32_e32 v41, 1.0, v41
	v_rcp_f32_e32 v40, v40
	v_rcp_f32_e32 v41, v41
	s_nop 0
	v_pk_mul_f32 v[38:39], v[40:41], v[38:39]
	s_nop 0
	v_pk_mul_f32 v[20:21], v[20:21], v[38:39]
	s_nop 0
	v_cvt_pk_bf16_f32 v19, v20, v21
	global_store_dwordx2 v[34:35], v[18:19], off
	global_load_dwordx2 v[18:19], v[36:37], off offset:16
	s_waitcnt vmcnt(0)
	v_lshlrev_b32_e32 v20, 16, v18
	v_and_b32_e32 v21, 0xffff0000, v18
	v_mul_f32_e32 v18, 0x3d372713, v20
	v_mul_f32_e32 v18, v18, v20
	v_mov_b32_e32 v38, v20
	v_fmac_f32_e32 v38, v18, v38
	v_mul_f32_e32 v18, 0x3f4c422a, v38
	v_add_f32_e32 v18, v18, v18
	v_mul_f32_e32 v18, 0xbfb8aa3b, v18
	v_exp_f32_e32 v18, v18
	v_mov_b32_e32 v39, v21
	v_add_f32_e32 v18, 1.0, v18
	v_rcp_f32_e32 v38, v18
	v_mul_f32_e32 v18, 0x3d372713, v21
	v_mul_f32_e32 v18, v18, v21
	v_fmac_f32_e32 v39, v18, v39
	v_mul_f32_e32 v18, 0x3f4c422a, v39
	v_add_f32_e32 v18, v18, v18
	v_mul_f32_e32 v18, 0xbfb8aa3b, v18
	v_exp_f32_e32 v18, v18
	s_nop 0
	v_add_f32_e32 v18, 1.0, v18
	v_rcp_f32_e32 v39, v18
	v_lshlrev_b32_e32 v18, 16, v19
	v_and_b32_e32 v19, 0xffff0000, v19
	v_pk_mul_f32 v[20:21], v[38:39], v[20:21]
	s_nop 0
	v_pk_mul_f32 v[20:21], v[22:23], v[20:21]
	v_mul_f32_e32 v22, 0x3d372713, v18
	v_mul_f32_e32 v22, v22, v18
	v_mov_b32_e32 v23, v18
	v_fmac_f32_e32 v23, v22, v23
	v_mul_f32_e32 v22, 0x3f4c422a, v23
	v_mul_f32_e32 v23, 0x3d372713, v19
	v_mul_f32_e32 v23, v23, v19
	v_mov_b32_e32 v38, v19
	v_fmac_f32_e32 v38, v23, v38
	v_mul_f32_e32 v23, 0x3f4c422a, v38
	v_add_f32_e32 v22, v22, v22
	v_add_f32_e32 v23, v23, v23
	v_mul_f32_e32 v22, 0xbfb8aa3b, v22
	v_mul_f32_e32 v23, 0xbfb8aa3b, v23
	v_exp_f32_e32 v22, v22
	v_exp_f32_e32 v23, v23
	v_cvt_pk_bf16_f32 v20, v20, v21
	v_add_f32_e32 v22, 1.0, v22
	v_add_f32_e32 v23, 1.0, v23
	v_rcp_f32_e32 v22, v22
	v_rcp_f32_e32 v23, v23
	s_nop 0
	v_pk_mul_f32 v[18:19], v[22:23], v[18:19]
	v_pk_add_f32 v[22:23], v[24:25], v[0:1] op_sel_hi:[1,0]
	s_nop 0
	v_pk_mul_f32 v[18:19], v[22:23], v[18:19]
	s_nop 0
	v_cvt_pk_bf16_f32 v21, v18, v19
	global_load_dwordx2 v[18:19], v[36:37], off offset:32
	s_nop 0
	global_store_dwordx2 v[34:35], v[20:21], off offset:16
	s_waitcnt vmcnt(1)
; __device__ __forceinline__ unsigned cvtpk(float lo, float hi) { f32x2_t v = {lo, hi}; bf16x2_t b = __builtin_convertvector(v, bf16x2_t); return __builtin_bit_cast(unsigned, b); }
; __device__ __forceinline__ float bflo(unsigned u) { return __uint_as_float(u << 16); }
; __device__ __forceinline__ float bfhi(unsigned u) { return __uint_as_float(u & 0xffff0000u); }
; __device__ __forceinline__ float geluf_(float x) { const float y = 0.7978845608028654f * (x + 0.044715f * x * x * x); return x * sigmoidf_(2.0f * y); }
; __device__ __forceinline__ void sgu_item(LAS unsigned char* lds, const bf16* PROJ, bf16* MIX, const float* lg, const float* lb, const float* ws_, const float* bs_, int item, int tid) {
;     ...
;         { const int t = 32 * wt + r32; const float bias = bs_[g * 128 + t]; const bf16* up = PROJ + (row0 + t) * NPROJ + 128 * g + 64 * wcg + 4 * hi; bf16* op = MIX + (row0 + t) * D + 128 * g + 64 * wcg + 4 * hi;
; #pragma unroll
;           for (int ct = 0; ct < 2; ++ct)
; #pragma unroll
;             for (int g4 = 0; g4 < 4; ++g4) { const u32x2 uw = *(const u32x2*)(up + 32 * ct + 8 * g4);
;                 const float o0 = geluf_(bflo(uw.x)) * (acc[ct][4 * g4] + bias), o1 = geluf_(bfhi(uw.x)) * (acc[ct][4 * g4 + 1] + bias), o2 = geluf_(bflo(uw.y)) * (acc[ct][4 * g4 + 2] + bias), o3 = geluf_(bfhi(uw.y)) * (acc[ct][4 * g4 + 3] + bias);
;                 u32x2 w; w.x = cvtpk(o0, o1); w.y = cvtpk(o2, o3); *(u32x2*)(op + 32 * ct + 8 * g4) = w; } }
	v_lshlrev_b32_e32 v20, 16, v18
	v_and_b32_e32 v21, 0xffff0000, v18
	v_mul_f32_e32 v18, 0x3d372713, v20
	v_mul_f32_e32 v18, v18, v20
	v_mov_b32_e32 v22, v20
	v_fmac_f32_e32 v22, v18, v22
	v_mul_f32_e32 v18, 0x3f4c422a, v22
	v_add_f32_e32 v18, v18, v18
	v_mul_f32_e32 v18, 0xbfb8aa3b, v18
	v_exp_f32_e32 v18, v18
	v_mov_b32_e32 v23, v21
	v_add_f32_e32 v18, 1.0, v18
	v_rcp_f32_e32 v22, v18
	v_mul_f32_e32 v18, 0x3d372713, v21
	v_mul_f32_e32 v18, v18, v21
	v_fmac_f32_e32 v23, v18, v23
	v_mul_f32_e32 v18, 0x3f4c422a, v23
	v_add_f32_e32 v18, v18, v18
	v_mul_f32_e32 v18, 0xbfb8aa3b, v18
	v_exp_f32_e32 v18, v18
	s_nop 0
	v_add_f32_e32 v18, 1.0, v18
	v_rcp_f32_e32 v23, v18
	v_lshlrev_b32_e32 v18, 16, v19
	v_and_b32_e32 v19, 0xffff0000, v19
	v_mov_b32_e32 v24, v19
	v_pk_mul_f32 v[20:21], v[22:23], v[20:21]
	v_pk_add_f32 v[22:23], v[26:27], v[0:1] op_sel_hi:[1,0]
	s_nop 0
	v_pk_mul_f32 v[20:21], v[22:23], v[20:21]
	v_mul_f32_e32 v22, 0x3d372713, v18
	v_mul_f32_e32 v22, v22, v18
	v_mov_b32_e32 v23, v18
	v_fmac_f32_e32 v23, v22, v23
	v_mul_f32_e32 v22, 0x3f4c422a, v23
	v_mul_f32_e32 v23, 0x3d372713, v19
	v_mul_f32_e32 v23, v23, v19
	v_fmac_f32_e32 v24, v23, v24
	v_mul_f32_e32 v23, 0x3f4c422a, v24
	v_add_f32_e32 v22, v22, v22
	v_add_f32_e32 v23, v23, v23
	v_mul_f32_e32 v22, 0xbfb8aa3b, v22
	v_mul_f32_e32 v23, 0xbfb8aa3b, v23
	v_exp_f32_e32 v22, v22
	v_exp_f32_e32 v23, v23
	v_cvt_pk_bf16_f32 v20, v20, v21
	v_add_f32_e32 v22, 1.0, v22
	v_add_f32_e32 v23, 1.0, v23
	v_rcp_f32_e32 v22, v22
	v_rcp_f32_e32 v23, v23
	s_nop 0
	v_pk_mul_f32 v[18:19], v[22:23], v[18:19]
	v_pk_add_f32 v[22:23], v[28:29], v[0:1] op_sel_hi:[1,0]
	s_nop 0
	v_pk_mul_f32 v[18:19], v[22:23], v[18:19]
	s_nop 0
	v_cvt_pk_bf16_f32 v21, v18, v19
	global_load_dwordx2 v[18:19], v[36:37], off offset:48
	s_nop 0
	global_store_dwordx2 v[34:35], v[20:21], off offset:32
	s_waitcnt vmcnt(1)
	v_lshlrev_b32_e32 v20, 16, v18
	v_and_b32_e32 v21, 0xffff0000, v18
	v_mul_f32_e32 v18, 0x3d372713, v20
	v_mul_f32_e32 v18, v18, v20
	v_mov_b32_e32 v22, v20
	v_fmac_f32_e32 v22, v18, v22
	v_mul_f32_e32 v18, 0x3f4c422a, v22
	v_add_f32_e32 v18, v18, v18
	v_mul_f32_e32 v18, 0xbfb8aa3b, v18
	v_exp_f32_e32 v18, v18
	v_mov_b32_e32 v23, v21
	v_add_f32_e32 v18, 1.0, v18
	v_rcp_f32_e32 v22, v18
	v_mul_f32_e32 v18, 0x3d372713, v21
	v_mul_f32_e32 v18, v18, v21
	v_fmac_f32_e32 v23, v18, v23
	v_mul_f32_e32 v18, 0x3f4c422a, v23
	v_add_f32_e32 v18, v18, v18
	v_mul_f32_e32 v18, 0xbfb8aa3b, v18
	v_exp_f32_e32 v18, v18
	s_nop 0
	v_add_f32_e32 v18, 1.0, v18
	v_rcp_f32_e32 v23, v18
	v_lshlrev_b32_e32 v18, 16, v19
	v_and_b32_e32 v19, 0xffff0000, v19
	v_mov_b32_e32 v24, v19
	v_pk_mul_f32 v[20:21], v[22:23], v[20:21]
	v_pk_add_f32 v[22:23], v[30:31], v[0:1] op_sel_hi:[1,0]
	s_nop 0
	v_pk_mul_f32 v[20:21], v[22:23], v[20:21]
	v_mul_f32_e32 v22, 0x3d372713, v18
	v_mul_f32_e32 v22, v22, v18
	v_mov_b32_e32 v23, v18
	v_fmac_f32_e32 v23, v22, v23
	v_mul_f32_e32 v22, 0x3f4c422a, v23
	v_mul_f32_e32 v23, 0x3d372713, v19
	v_mul_f32_e32 v23, v23, v19
	v_fmac_f32_e32 v24, v23, v24
	v_mul_f32_e32 v23, 0x3f4c422a, v24
	v_add_f32_e32 v22, v22, v22
	v_add_f32_e32 v23, v23, v23
	v_mul_f32_e32 v22, 0xbfb8aa3b, v22
	v_mul_f32_e32 v23, 0xbfb8aa3b, v23
	v_exp_f32_e32 v22, v22
	v_exp_f32_e32 v23, v23
	v_cvt_pk_bf16_f32 v20, v20, v21
	v_add_f32_e32 v22, 1.0, v22
	v_add_f32_e32 v23, 1.0, v23
	v_rcp_f32_e32 v22, v22
	v_rcp_f32_e32 v23, v23
	s_nop 0
	v_pk_mul_f32 v[18:19], v[22:23], v[18:19]
	v_pk_add_f32 v[22:23], v[32:33], v[0:1] op_sel_hi:[1,0]
	s_nop 0
	v_pk_mul_f32 v[18:19], v[22:23], v[18:19]
	s_nop 0
	v_cvt_pk_bf16_f32 v21, v18, v19
	global_load_dwordx2 v[18:19], v[36:37], off offset:64
	s_nop 0
	global_store_dwordx2 v[34:35], v[20:21], off offset:48
	s_waitcnt vmcnt(1)
	v_lshlrev_b32_e32 v20, 16, v18
	v_and_b32_e32 v21, 0xffff0000, v18
	v_mul_f32_e32 v18, 0x3d372713, v20
	v_mul_f32_e32 v18, v18, v20
	v_mov_b32_e32 v22, v20
	v_fmac_f32_e32 v22, v18, v22
	v_mul_f32_e32 v18, 0x3f4c422a, v22
	v_add_f32_e32 v18, v18, v18
	v_mul_f32_e32 v18, 0xbfb8aa3b, v18
	v_exp_f32_e32 v18, v18
	v_mov_b32_e32 v23, v21
	v_add_f32_e32 v18, 1.0, v18
	v_rcp_f32_e32 v22, v18
	v_mul_f32_e32 v18, 0x3d372713, v21
	v_mul_f32_e32 v18, v18, v21
	v_fmac_f32_e32 v23, v18, v23
	v_mul_f32_e32 v18, 0x3f4c422a, v23
	v_add_f32_e32 v18, v18, v18
	v_mul_f32_e32 v18, 0xbfb8aa3b, v18
	v_exp_f32_e32 v18, v18
	s_nop 0
	v_add_f32_e32 v18, 1.0, v18
	v_rcp_f32_e32 v23, v18
	v_lshlrev_b32_e32 v18, 16, v19
	v_and_b32_e32 v19, 0xffff0000, v19
	v_pk_mul_f32 v[20:21], v[22:23], v[20:21]
	s_nop 0
	v_pk_mul_f32 v[2:3], v[2:3], v[20:21]
	v_mul_f32_e32 v20, 0x3d372713, v18
	v_mul_f32_e32 v20, v20, v18
	v_mov_b32_e32 v21, v18
	v_fmac_f32_e32 v21, v20, v21
	v_mul_f32_e32 v20, 0x3f4c422a, v21
	v_mul_f32_e32 v21, 0x3d372713, v19
	v_mul_f32_e32 v21, v21, v19
	v_mov_b32_e32 v22, v19
	v_fmac_f32_e32 v22, v21, v22
	v_mul_f32_e32 v21, 0x3f4c422a, v22
	v_add_f32_e32 v20, v20, v20
	v_add_f32_e32 v21, v21, v21
	v_mul_f32_e32 v20, 0xbfb8aa3b, v20
	v_mul_f32_e32 v21, 0xbfb8aa3b, v21
	v_exp_f32_e32 v20, v20
	v_exp_f32_e32 v21, v21
	v_cvt_pk_bf16_f32 v2, v2, v3
	v_add_f32_e32 v20, 1.0, v20
	v_add_f32_e32 v21, 1.0, v21
	v_rcp_f32_e32 v20, v20
	v_rcp_f32_e32 v21, v21
	s_nop 0
	v_pk_mul_f32 v[18:19], v[20:21], v[18:19]
	s_nop 0
	v_pk_mul_f32 v[4:5], v[4:5], v[18:19]
	s_nop 0
	v_cvt_pk_bf16_f32 v3, v4, v5
	global_store_dwordx2 v[34:35], v[2:3], off offset:64
	global_load_dwordx2 v[2:3], v[36:37], off offset:80
	s_waitcnt vmcnt(0)
; __device__ __forceinline__ unsigned cvtpk(float lo, float hi) { f32x2_t v = {lo, hi}; bf16x2_t b = __builtin_convertvector(v, bf16x2_t); return __builtin_bit_cast(unsigned, b); }
; __device__ __forceinline__ float bflo(unsigned u) { return __uint_as_float(u << 16); }
; __device__ __forceinline__ float bfhi(unsigned u) { return __uint_as_float(u & 0xffff0000u); }
; __device__ __forceinline__ float geluf_(float x) { const float y = 0.7978845608028654f * (x + 0.044715f * x * x * x); return x * sigmoidf_(2.0f * y); }
; __device__ __forceinline__ void sgu_item(LAS unsigned char* lds, const bf16* PROJ, bf16* MIX, const float* lg, const float* lb, const float* ws_, const float* bs_, int item, int tid) {
;     ...
;         { const int t = 32 * wt + r32; const float bias = bs_[g * 128 + t]; const bf16* up = PROJ + (row0 + t) * NPROJ + 128 * g + 64 * wcg + 4 * hi; bf16* op = MIX + (row0 + t) * D + 128 * g + 64 * wcg + 4 * hi;
; #pragma unroll
;           for (int ct = 0; ct < 2; ++ct)
; #pragma unroll
;             for (int g4 = 0; g4 < 4; ++g4) { const u32x2 uw = *(const u32x2*)(up + 32 * ct + 8 * g4);
;                 const float o0 = geluf_(bflo(uw.x)) * (acc[ct][4 * g4] + bias), o1 = geluf_(bfhi(uw.x)) * (acc[ct][4 * g4 + 1] + bias), o2 = geluf_(bflo(uw.y)) * (acc[ct][4 * g4 + 2] + bias), o3 = geluf_(bfhi(uw.y)) * (acc[ct][4 * g4 + 3] + bias);
;                 u32x2 w; w.x = cvtpk(o0, o1); w.y = cvtpk(o2, o3); *(u32x2*)(op + 32 * ct + 8 * g4) = w; } }
;         __syncthreads();
	v_lshlrev_b32_e32 v4, 16, v2
	v_and_b32_e32 v5, 0xffff0000, v2
	v_mul_f32_e32 v2, 0x3d372713, v4
	v_mul_f32_e32 v2, v2, v4
	v_mov_b32_e32 v18, v4
	v_fmac_f32_e32 v18, v2, v18
	v_mul_f32_e32 v2, 0x3f4c422a, v18
	v_add_f32_e32 v2, v2, v2
	v_mul_f32_e32 v2, 0xbfb8aa3b, v2
	v_exp_f32_e32 v2, v2
	v_mov_b32_e32 v19, v5
	v_add_f32_e32 v2, 1.0, v2
	v_rcp_f32_e32 v18, v2
	v_mul_f32_e32 v2, 0x3d372713, v5
	v_mul_f32_e32 v2, v2, v5
	v_fmac_f32_e32 v19, v2, v19
	v_mul_f32_e32 v2, 0x3f4c422a, v19
	v_add_f32_e32 v2, v2, v2
	v_mul_f32_e32 v2, 0xbfb8aa3b, v2
	v_exp_f32_e32 v2, v2
	s_nop 0
	v_add_f32_e32 v2, 1.0, v2
	v_rcp_f32_e32 v19, v2
	v_lshlrev_b32_e32 v2, 16, v3
	v_and_b32_e32 v3, 0xffff0000, v3
	v_pk_mul_f32 v[4:5], v[18:19], v[4:5]
	s_nop 0
	v_pk_mul_f32 v[4:5], v[6:7], v[4:5]
	v_mul_f32_e32 v6, 0x3d372713, v2
	v_mul_f32_e32 v6, v6, v2
	v_mov_b32_e32 v7, v2
	v_fmac_f32_e32 v7, v6, v7
	v_mul_f32_e32 v6, 0x3f4c422a, v7
	v_mul_f32_e32 v7, 0x3d372713, v3
	v_mul_f32_e32 v7, v7, v3
	v_mov_b32_e32 v18, v3
	v_fmac_f32_e32 v18, v7, v18
	v_mul_f32_e32 v7, 0x3f4c422a, v18
	v_add_f32_e32 v6, v6, v6
	v_add_f32_e32 v7, v7, v7
	v_mul_f32_e32 v6, 0xbfb8aa3b, v6
	v_mul_f32_e32 v7, 0xbfb8aa3b, v7
	v_exp_f32_e32 v6, v6
	v_exp_f32_e32 v7, v7
	v_cvt_pk_bf16_f32 v4, v4, v5
	v_add_f32_e32 v6, 1.0, v6
	v_add_f32_e32 v7, 1.0, v7
	v_rcp_f32_e32 v6, v6
	v_rcp_f32_e32 v7, v7
	s_nop 0
	v_pk_mul_f32 v[2:3], v[6:7], v[2:3]
	v_pk_add_f32 v[6:7], v[8:9], v[0:1] op_sel_hi:[1,0]
	s_nop 0
	v_pk_mul_f32 v[2:3], v[6:7], v[2:3]
	s_nop 0
	v_cvt_pk_bf16_f32 v5, v2, v3
	global_load_dwordx2 v[2:3], v[36:37], off offset:96
	s_nop 0
	global_store_dwordx2 v[34:35], v[4:5], off offset:80
	s_waitcnt vmcnt(1)
	v_lshlrev_b32_e32 v4, 16, v2
	v_and_b32_e32 v5, 0xffff0000, v2
	v_mul_f32_e32 v2, 0x3d372713, v4
	v_mul_f32_e32 v2, v2, v4
	v_mov_b32_e32 v6, v4
	v_fmac_f32_e32 v6, v2, v6
	v_mul_f32_e32 v2, 0x3f4c422a, v6
	v_add_f32_e32 v2, v2, v2
	v_mul_f32_e32 v2, 0xbfb8aa3b, v2
	v_exp_f32_e32 v2, v2
	v_mov_b32_e32 v7, v5
	v_add_f32_e32 v2, 1.0, v2
	v_rcp_f32_e32 v6, v2
	v_mul_f32_e32 v2, 0x3d372713, v5
	v_mul_f32_e32 v2, v2, v5
	v_fmac_f32_e32 v7, v2, v7
	v_mul_f32_e32 v2, 0x3f4c422a, v7
	v_add_f32_e32 v2, v2, v2
	v_mul_f32_e32 v2, 0xbfb8aa3b, v2
	v_exp_f32_e32 v2, v2
	s_nop 0
	v_add_f32_e32 v2, 1.0, v2
	v_rcp_f32_e32 v7, v2
	v_lshlrev_b32_e32 v2, 16, v3
	v_and_b32_e32 v3, 0xffff0000, v3
	v_mov_b32_e32 v8, v3
	v_pk_mul_f32 v[4:5], v[6:7], v[4:5]
	v_pk_add_f32 v[6:7], v[10:11], v[0:1] op_sel_hi:[1,0]
	s_nop 0
	v_pk_mul_f32 v[4:5], v[6:7], v[4:5]
	v_mul_f32_e32 v6, 0x3d372713, v2
	v_mul_f32_e32 v6, v6, v2
	v_mov_b32_e32 v7, v2
	v_fmac_f32_e32 v7, v6, v7
	v_mul_f32_e32 v6, 0x3f4c422a, v7
	v_mul_f32_e32 v7, 0x3d372713, v3
	v_mul_f32_e32 v7, v7, v3
	v_fmac_f32_e32 v8, v7, v8
	v_mul_f32_e32 v7, 0x3f4c422a, v8
	v_add_f32_e32 v6, v6, v6
	v_add_f32_e32 v7, v7, v7
	v_mul_f32_e32 v6, 0xbfb8aa3b, v6
	v_mul_f32_e32 v7, 0xbfb8aa3b, v7
	v_exp_f32_e32 v6, v6
	v_exp_f32_e32 v7, v7
	v_cvt_pk_bf16_f32 v4, v4, v5
	v_add_f32_e32 v6, 1.0, v6
	v_add_f32_e32 v7, 1.0, v7
	v_rcp_f32_e32 v6, v6
	v_rcp_f32_e32 v7, v7
	s_nop 0
	v_pk_mul_f32 v[2:3], v[6:7], v[2:3]
	v_pk_add_f32 v[6:7], v[12:13], v[0:1] op_sel_hi:[1,0]
	s_nop 0
	v_pk_mul_f32 v[2:3], v[6:7], v[2:3]
	s_nop 0
	v_cvt_pk_bf16_f32 v5, v2, v3
	global_load_dwordx2 v[2:3], v[36:37], off offset:112
	s_nop 0
	global_store_dwordx2 v[34:35], v[4:5], off offset:96
	s_waitcnt vmcnt(1)
	v_lshlrev_b32_e32 v4, 16, v2
	v_and_b32_e32 v5, 0xffff0000, v2
	v_mul_f32_e32 v2, 0x3d372713, v4
	v_mul_f32_e32 v2, v2, v4
	v_mov_b32_e32 v6, v4
	v_fmac_f32_e32 v6, v2, v6
	v_mul_f32_e32 v2, 0x3f4c422a, v6
	v_add_f32_e32 v2, v2, v2
	v_mul_f32_e32 v2, 0xbfb8aa3b, v2
	v_exp_f32_e32 v2, v2
	v_mov_b32_e32 v7, v5
	v_add_f32_e32 v2, 1.0, v2
	v_rcp_f32_e32 v6, v2
	v_mul_f32_e32 v2, 0x3d372713, v5
	v_mul_f32_e32 v2, v2, v5
	v_fmac_f32_e32 v7, v2, v7
	v_mul_f32_e32 v2, 0x3f4c422a, v7
	v_add_f32_e32 v2, v2, v2
	v_mul_f32_e32 v2, 0xbfb8aa3b, v2
	v_exp_f32_e32 v2, v2
	s_nop 0
	v_add_f32_e32 v2, 1.0, v2
	v_rcp_f32_e32 v7, v2
	v_lshlrev_b32_e32 v2, 16, v3
	v_and_b32_e32 v3, 0xffff0000, v3
	v_mov_b32_e32 v8, v3
	v_pk_mul_f32 v[4:5], v[6:7], v[4:5]
	v_pk_add_f32 v[6:7], v[14:15], v[0:1] op_sel_hi:[1,0]
	s_nop 0
	v_pk_mul_f32 v[4:5], v[6:7], v[4:5]
	v_mul_f32_e32 v6, 0x3d372713, v2
	v_mul_f32_e32 v6, v6, v2
	v_mov_b32_e32 v7, v2
	v_fmac_f32_e32 v7, v6, v7
	v_mul_f32_e32 v6, 0x3f4c422a, v7
	v_mul_f32_e32 v7, 0x3d372713, v3
	v_mul_f32_e32 v7, v7, v3
	v_fmac_f32_e32 v8, v7, v8
	v_mul_f32_e32 v7, 0x3f4c422a, v8
	v_add_f32_e32 v6, v6, v6
	v_add_f32_e32 v7, v7, v7
	v_mul_f32_e32 v6, 0xbfb8aa3b, v6
	v_mul_f32_e32 v7, 0xbfb8aa3b, v7
	v_exp_f32_e32 v6, v6
	v_exp_f32_e32 v7, v7
	v_cvt_pk_bf16_f32 v4, v4, v5
	v_add_f32_e32 v6, 1.0, v6
	v_add_f32_e32 v7, 1.0, v7
	v_rcp_f32_e32 v6, v6
	v_rcp_f32_e32 v7, v7
	s_nop 0
	v_pk_mul_f32 v[2:3], v[6:7], v[2:3]
	v_pk_add_f32 v[6:7], v[16:17], v[0:1] op_sel_hi:[1,0]
	s_nop 0
	v_pk_mul_f32 v[2:3], v[6:7], v[2:3]
	s_nop 0
	v_cvt_pk_bf16_f32 v5, v2, v3
	global_store_dwordx2 v[34:35], v[4:5], off offset:112
	s_barrier
	s_cbranch_scc0 .LBB0_363
